# norm2 context rows: all 32 loads of a row (x, 4 split-K partials, gamma/scale/shift) in flight at once
# speedup vs baseline: 1.0610x; 1.0009x over previous
; template <int NP> __device__ __forceinline__ void mod_row(float* xrow, const float* prow, const float* g, const float* sh, const float* sc, bf16_t* orow, int lane) {
;     f32x4 v[4]; float s = 0.f;
; #pragma unroll
;     for (int j = 0; j < 4; ++j) { v[j] = *(const f32x4*)(xrow + 4 * lane + 256 * j);
;         if (NP > 0) {
; #pragma unroll
;             for (int q = 0; q < NP; ++q) v[j] = v[j] + *(const f32x4*)(prow + (size_t)q * MC * DM + 4 * lane + 256 * j);
; __device__ __forceinline__ void ph_norm2(int li) {
;     ...
;     for (int row = gw; row < MR; row += NGW) {
;         const int mi = row < ML ? row >> 11 : 8;
;         if (row < ML) mod_row<0>(XL + (size_t)row * DM, nullptr, g2, md + mi * 6144 + 3 * 1024, md + mi * 6144 + 4 * 1024, H + (size_t)row * DM, lane);
;         else mod_row<4>(XC + (size_t)(row - ML) * DM, (const float*)(R + 36 * MiB) + (size_t)(row - ML) * DM, g2, md + mi * 6144 + 3 * 1024, md + mi * 6144 + 4 * 1024, H + (size_t)row * DM, lane);
.LBB0_58:
	s_min_i32 s2, s38, 0x4000
	s_ashr_i32 s4, s2, 11
	s_cmpk_gt_i32 s38, 0x3fff
	s_mov_b64 s[2:3], -1
	s_mul_i32 s16, s4, 0x1800
	v_lshlrev_b32_e32 v48, 2, v16
	v_lshlrev_b32_e32 v44, 1, v16
	v_lshlrev_b32_e32 v47, 2, v24
	v_lshlrev_b32_e32 v46, 2, v26
	v_lshlrev_b32_e32 v45, 2, v28
	s_cbranch_scc0 .LBB0_60
	s_mov_b32 s17, s23
	s_add_i32 s22, s38, 0xffffc000
	s_lshl_b64 s[2:3], s[16:17], 2
	s_add_u32 s2, s59, s2
	s_addc_u32 s3, s60, s3
	s_add_u32 s50, s2, 0x3000
	s_addc_u32 s51, s3, 0
	s_add_u32 s54, s2, 0x4000
	s_mov_b32 s39, s23
	s_addc_u32 s55, s3, 0
	s_lshl_b64 s[2:3], s[38:39], 11
	s_add_u32 s48, s57, s2
	s_addc_u32 s49, s58, s3
	s_lshl_b64 s[2:3], s[22:23], 12
	v_lshl_add_u64 v[32:33], v[18:19], 0, s[2:3]
	v_lshl_add_u64 v[40:41], v[20:21], 0, s[2:3]
	v_add_co_u32_e32 v168, vcc, s15, v40
	s_mov_b32 s2, 0x1000000
	s_nop 0
	v_addc_co_u32_e32 v169, vcc, 0, v41, vcc
	v_add_co_u32_e32 v170, vcc, s2, v40
	s_mov_b32 s2, 0x1800000
	s_nop 0
	v_addc_co_u32_e32 v171, vcc, 0, v41, vcc
	v_add_co_u32_e32 v172, vcc, s2, v40
	s_nop 1
	v_addc_co_u32_e32 v173, vcc, 0, v41, vcc

; __device__ __forceinline__ unsigned cvt_pk_bf16(float lo, float hi) { unsigned r; asm volatile("v_cvt_pk_bf16_f32 %0, %1, %2" : "=v"(r) : "v"(lo), "v"(hi)); return r; }
; template <int NP> __device__ __forceinline__ void mod_row(float* xrow, const float* prow, const float* g, const float* sh, const float* sc, bf16_t* orow, int lane) {
;     f32x4 v[4]; float s = 0.f;
; #pragma unroll
;     for (int j = 0; j < 4; ++j) { v[j] = *(const f32x4*)(xrow + 4 * lane + 256 * j);
;         if (NP > 0) {
; #pragma unroll
;             for (int q = 0; q < NP; ++q) v[j] = v[j] + *(const f32x4*)(prow + (size_t)q * MC * DM + 4 * lane + 256 * j);
;             *(f32x4*)(xrow + 4 * lane + 256 * j) = v[j]; }
;         s += (v[j].x * v[j].x + v[j].y * v[j].y) + (v[j].z * v[j].z + v[j].w * v[j].w); }
;     const float rstd = rsqrtf(wave_sum(s, lane) * (1.f / DM) + EPSV);
; #pragma unroll
;     for (int j = 0; j < 4; ++j) {
;         const int c = 4 * lane + 256 * j;
;         const f32x4 gg = *(const f32x4*)(g + c), ss = *(const f32x4*)(sc + c), hh = *(const f32x4*)(sh + c);
;         const f32x4 o = v[j] * rstd * gg * (ss + 1.0f) + hh;
;         u32x2 w; w.x = cvt_pk_bf16(o.x, o.y); w.y = cvt_pk_bf16(o.z, o.w);
;         *(u32x2*)(orow + c) = w;
	global_load_dwordx4 v[0:3], v[32:33], off
	global_load_dwordx4 v[104:107], v[40:41], off
	global_load_dwordx4 v[120:123], v[168:169], off
	global_load_dwordx4 v[136:139], v[170:171], off
	global_load_dwordx4 v[152:155], v[172:173], off
	global_load_dwordx4 v[4:7], v[32:33], off offset:1024
	global_load_dwordx4 v[108:111], v[40:41], off offset:1024
	global_load_dwordx4 v[124:127], v[168:169], off offset:1024
	global_load_dwordx4 v[140:143], v[170:171], off offset:1024
	global_load_dwordx4 v[156:159], v[172:173], off offset:1024
	global_load_dwordx4 v[8:11], v[32:33], off offset:2048
	global_load_dwordx4 v[112:115], v[40:41], off offset:2048
	global_load_dwordx4 v[128:131], v[168:169], off offset:2048
	global_load_dwordx4 v[144:147], v[170:171], off offset:2048
	global_load_dwordx4 v[160:163], v[172:173], off offset:2048
	global_load_dwordx4 v[12:15], v[32:33], off offset:3072
	global_load_dwordx4 v[116:119], v[40:41], off offset:3072
	global_load_dwordx4 v[132:135], v[168:169], off offset:3072
	global_load_dwordx4 v[148:151], v[170:171], off offset:3072
	global_load_dwordx4 v[164:167], v[172:173], off offset:3072
	global_load_dwordx4 v[52:55], v[22:23], off
	global_load_dwordx4 v[56:59], v48, s[54:55]
	global_load_dwordx4 v[60:63], v48, s[50:51]
	global_load_dwordx4 v[64:67], v[22:23], off offset:1024
	global_load_dwordx4 v[68:71], v47, s[54:55]
	global_load_dwordx4 v[72:75], v47, s[50:51]
	global_load_dwordx4 v[76:79], v[22:23], off offset:2048
	global_load_dwordx4 v[80:83], v46, s[54:55]
	global_load_dwordx4 v[84:87], v46, s[50:51]
	global_load_dwordx4 v[88:91], v[22:23], off offset:3072
	global_load_dwordx4 v[92:95], v45, s[54:55]
	global_load_dwordx4 v[96:99], v45, s[50:51]
	s_waitcnt vmcnt(27)
	v_pk_add_f32 v[2:3], v[2:3], v[106:107]
	v_pk_add_f32 v[0:1], v[0:1], v[104:105]
	v_pk_add_f32 v[2:3], v[2:3], v[122:123]
	v_pk_add_f32 v[0:1], v[0:1], v[120:121]
	v_pk_add_f32 v[2:3], v[2:3], v[138:139]
	v_pk_add_f32 v[0:1], v[0:1], v[136:137]
	v_pk_add_f32 v[2:3], v[2:3], v[154:155]
	v_pk_add_f32 v[0:1], v[0:1], v[152:153]
	s_waitcnt vmcnt(22)
	v_pk_add_f32 v[6:7], v[6:7], v[110:111]
	v_pk_add_f32 v[4:5], v[4:5], v[108:109]
	v_pk_add_f32 v[6:7], v[6:7], v[126:127]
	v_pk_add_f32 v[4:5], v[4:5], v[124:125]
	v_pk_add_f32 v[6:7], v[6:7], v[142:143]
	v_pk_add_f32 v[4:5], v[4:5], v[140:141]
	v_pk_add_f32 v[6:7], v[6:7], v[158:159]
	v_pk_add_f32 v[4:5], v[4:5], v[156:157]
	s_waitcnt vmcnt(17)
	v_pk_add_f32 v[10:11], v[10:11], v[114:115]
	v_pk_add_f32 v[8:9], v[8:9], v[112:113]
	v_pk_add_f32 v[10:11], v[10:11], v[130:131]
	v_pk_add_f32 v[8:9], v[8:9], v[128:129]
	v_pk_add_f32 v[10:11], v[10:11], v[146:147]
	v_pk_add_f32 v[8:9], v[8:9], v[144:145]
	v_pk_add_f32 v[10:11], v[10:11], v[162:163]
	v_pk_add_f32 v[8:9], v[8:9], v[160:161]
	s_waitcnt vmcnt(12)
	v_pk_add_f32 v[14:15], v[14:15], v[118:119]
	v_pk_add_f32 v[12:13], v[12:13], v[116:117]
	v_pk_add_f32 v[14:15], v[14:15], v[134:135]
	v_pk_add_f32 v[12:13], v[12:13], v[132:133]
	v_pk_add_f32 v[14:15], v[14:15], v[150:151]
	v_pk_add_f32 v[12:13], v[12:13], v[148:149]
	v_pk_add_f32 v[14:15], v[14:15], v[166:167]
	v_pk_add_f32 v[12:13], v[12:13], v[164:165]
	global_store_dwordx4 v[32:33], v[0:3], off
	global_store_dwordx4 v[32:33], v[4:7], off offset:1024
	global_store_dwordx4 v[32:33], v[8:11], off offset:2048
	global_store_dwordx4 v[32:33], v[12:15], off offset:3072
	v_pk_mul_f32 v[36:37], v[2:3], v[2:3]
	v_pk_mul_f32 v[38:39], v[0:1], v[0:1]
	s_nop 0
	v_pk_mov_b32 v[40:41], v[38:39], v[36:37] op_sel:[1,0]
	v_mov_b32_e32 v39, v37
	v_pk_add_f32 v[32:33], v[40:41], v[38:39]
	v_pk_mul_f32 v[36:37], v[6:7], v[6:7]
	v_pk_mul_f32 v[38:39], v[4:5], v[4:5]
	v_pk_add_f32 v[32:33], v[32:33], v[32:33] op_sel:[0,1] op_sel_hi:[1,0]
	v_pk_mov_b32 v[40:41], v[38:39], v[36:37] op_sel:[1,0]
	v_mov_b32_e32 v39, v37
	v_pk_add_f32 v[34:35], v[40:41], v[38:39]
	s_nop 1
	v_pk_add_f32 v[34:35], v[34:35], v[34:35] op_sel:[0,1] op_sel_hi:[1,0]
	v_mul_f32_e32 v36, v12, v12
	v_mul_f32_e32 v37, v13, v13
	v_mov_b32_e32 v33, v36
	v_mov_b32_e32 v35, v37
	v_pk_add_f32 v[32:33], v[32:33], v[34:35]
	v_mul_f32_e32 v34, v9, v9
	v_mul_f32_e32 v36, v11, v11
	v_mul_f32_e32 v38, v14, v14
	v_mul_f32_e32 v39, v15, v15
	v_pk_fma_f32 v[34:35], v[8:9], v[8:9], v[34:35] op_sel_hi:[1,1,0]
	v_pk_fma_f32 v[36:37], v[10:11], v[10:11], v[36:37] op_sel_hi:[1,1,0]
	v_mov_b32_e32 v35, v38
	v_mov_b32_e32 v37, v39
	v_pk_add_f32 v[34:35], v[34:35], v[36:37]
	s_nop 0
	v_pk_add_f32 v[32:33], v[32:33], v[34:35]
	s_nop 1
	v_add_f32_e32 v32, v32, v33
	ds_bpermute_b32 v33, v17, v32
	s_waitcnt lgkmcnt(0)
	v_add_f32_e32 v32, v32, v33
	ds_bpermute_b32 v33, v25, v32
	s_waitcnt lgkmcnt(0)
	v_add_f32_e32 v32, v32, v33
	ds_bpermute_b32 v33, v27, v32
	s_waitcnt lgkmcnt(0)
	v_add_f32_e32 v32, v32, v33
	ds_bpermute_b32 v33, v29, v32
	s_waitcnt lgkmcnt(0)
	v_add_f32_e32 v32, v32, v33
	ds_bpermute_b32 v33, v42, v32
	s_waitcnt lgkmcnt(0)
	v_add_f32_e32 v32, v32, v33
	ds_bpermute_b32 v33, v43, v32
	s_waitcnt lgkmcnt(0)
	v_add_f32_e32 v32, v32, v33
	v_fmamk_f32 v32, v32, 0x3a800000, v195
	v_cmp_gt_f32_e32 vcc, s15, v32
	v_mul_f32_e32 v33, 0x4b800000, v32
	s_nop 0
	v_cndmask_b32_e32 v32, v32, v33, vcc
	v_rsq_f32_e32 v32, v32
	s_nop 0
	v_mul_f32_e32 v33, 0x45800000, v32
	v_cndmask_b32_e32 v32, v32, v33, vcc
	v_pk_mul_f32 v[2:3], v[2:3], v[32:33] op_sel_hi:[1,0]
	v_pk_mul_f32 v[0:1], v[0:1], v[32:33] op_sel_hi:[1,0]
	v_pk_mul_f32 v[6:7], v[6:7], v[32:33] op_sel_hi:[1,0]
	v_pk_mul_f32 v[4:5], v[4:5], v[32:33] op_sel_hi:[1,0]
	v_pk_mul_f32 v[8:9], v[8:9], v[32:33] op_sel_hi:[1,0]
	v_pk_mul_f32 v[10:11], v[10:11], v[32:33] op_sel_hi:[1,0]
	v_pk_mul_f32 v[12:13], v[12:13], v[32:33] op_sel_hi:[1,0]
	v_pk_mul_f32 v[14:15], v[14:15], v[32:33] op_sel_hi:[1,0]

; __device__ __forceinline__ unsigned cvt_pk_bf16(float lo, float hi) { unsigned r; asm volatile("v_cvt_pk_bf16_f32 %0, %1, %2" : "=v"(r) : "v"(lo), "v"(hi)); return r; }
; template <int NP> __device__ __forceinline__ void mod_row(float* xrow, const float* prow, const float* g, const float* sh, const float* sc, bf16_t* orow, int lane) {
;     ...
;     for (int j = 0; j < 4; ++j) {
;         const int c = 4 * lane + 256 * j;
;         const f32x4 gg = *(const f32x4*)(g + c), ss = *(const f32x4*)(sc + c), hh = *(const f32x4*)(sh + c);
;         const f32x4 o = v[j] * rstd * gg * (ss + 1.0f) + hh;
;         u32x2 w; w.x = cvt_pk_bf16(o.x, o.y); w.y = cvt_pk_bf16(o.z, o.w);
;         *(u32x2*)(orow + c) = w;
	s_waitcnt vmcnt(13)
	v_pk_mul_f32 v[0:1], v[52:53], v[0:1]
	v_pk_mul_f32 v[2:3], v[54:55], v[2:3]
	v_pk_add_f32 v[36:37], v[56:57], 1.0 op_sel_hi:[1,0]
	v_pk_add_f32 v[34:35], v[58:59], 1.0 op_sel_hi:[1,0]
	v_pk_fma_f32 v[0:1], v[36:37], v[0:1], v[60:61]
	s_nop 0
	v_pk_fma_f32 v[2:3], v[34:35], v[2:3], v[62:63]
	s_nop 0
	v_cvt_pk_bf16_f32 v174, v0, v1
	s_nop 0
	v_cvt_pk_bf16_f32 v175, v2, v3

; __device__ __forceinline__ unsigned cvt_pk_bf16(float lo, float hi) { unsigned r; asm volatile("v_cvt_pk_bf16_f32 %0, %1, %2" : "=v"(r) : "v"(lo), "v"(hi)); return r; }
; template <int NP> __device__ __forceinline__ void mod_row(float* xrow, const float* prow, const float* g, const float* sh, const float* sc, bf16_t* orow, int lane) {
;     ...
;     for (int j = 0; j < 4; ++j) {
;         const int c = 4 * lane + 256 * j;
;         const f32x4 gg = *(const f32x4*)(g + c), ss = *(const f32x4*)(sc + c), hh = *(const f32x4*)(sh + c);
;         const f32x4 o = v[j] * rstd * gg * (ss + 1.0f) + hh;
;         u32x2 w; w.x = cvt_pk_bf16(o.x, o.y); w.y = cvt_pk_bf16(o.z, o.w);
;         *(u32x2*)(orow + c) = w;
	global_store_dwordx2 v44, v[174:175], s[48:49]
	s_waitcnt vmcnt(11)
	v_pk_mul_f32 v[4:5], v[64:65], v[4:5]
	v_pk_mul_f32 v[6:7], v[66:67], v[6:7]
	v_pk_add_f32 v[36:37], v[68:69], 1.0 op_sel_hi:[1,0]
	v_pk_add_f32 v[34:35], v[70:71], 1.0 op_sel_hi:[1,0]
	v_pk_fma_f32 v[4:5], v[36:37], v[4:5], v[72:73]
	s_nop 0
	v_pk_fma_f32 v[6:7], v[34:35], v[6:7], v[74:75]
	s_nop 0
	v_cvt_pk_bf16_f32 v176, v4, v5
	s_nop 0
	v_cvt_pk_bf16_f32 v177, v6, v7

; __device__ __forceinline__ unsigned cvt_pk_bf16(float lo, float hi) { unsigned r; asm volatile("v_cvt_pk_bf16_f32 %0, %1, %2" : "=v"(r) : "v"(lo), "v"(hi)); return r; }
; template <int NP> __device__ __forceinline__ void mod_row(float* xrow, const float* prow, const float* g, const float* sh, const float* sc, bf16_t* orow, int lane) {
;     ...
;     for (int j = 0; j < 4; ++j) {
;         const int c = 4 * lane + 256 * j;
;         const f32x4 gg = *(const f32x4*)(g + c), ss = *(const f32x4*)(sc + c), hh = *(const f32x4*)(sh + c);
;         const f32x4 o = v[j] * rstd * gg * (ss + 1.0f) + hh;
;         u32x2 w; w.x = cvt_pk_bf16(o.x, o.y); w.y = cvt_pk_bf16(o.z, o.w);
;         *(u32x2*)(orow + c) = w;
	global_store_dwordx2 v44, v[176:177], s[48:49] offset:512
	s_waitcnt vmcnt(9)
	v_pk_mul_f32 v[8:9], v[76:77], v[8:9]
	v_pk_mul_f32 v[10:11], v[78:79], v[10:11]
	v_pk_add_f32 v[36:37], v[80:81], 1.0 op_sel_hi:[1,0]
	v_pk_add_f32 v[34:35], v[82:83], 1.0 op_sel_hi:[1,0]
	v_pk_fma_f32 v[8:9], v[36:37], v[8:9], v[84:85]
	s_nop 0
	v_pk_fma_f32 v[10:11], v[34:35], v[10:11], v[86:87]
	s_nop 0
	v_cvt_pk_bf16_f32 v178, v8, v9
	s_nop 0
	v_cvt_pk_bf16_f32 v179, v10, v11

; __device__ __forceinline__ unsigned cvt_pk_bf16(float lo, float hi) { unsigned r; asm volatile("v_cvt_pk_bf16_f32 %0, %1, %2" : "=v"(r) : "v"(lo), "v"(hi)); return r; }
; template <int NP> __device__ __forceinline__ void mod_row(float* xrow, const float* prow, const float* g, const float* sh, const float* sc, bf16_t* orow, int lane) {
;     ...
;     for (int j = 0; j < 4; ++j) {
;         const int c = 4 * lane + 256 * j;
;         const f32x4 gg = *(const f32x4*)(g + c), ss = *(const f32x4*)(sc + c), hh = *(const f32x4*)(sh + c);
;         const f32x4 o = v[j] * rstd * gg * (ss + 1.0f) + hh;
;         u32x2 w; w.x = cvt_pk_bf16(o.x, o.y); w.y = cvt_pk_bf16(o.z, o.w);
;         *(u32x2*)(orow + c) = w;
	global_store_dwordx2 v44, v[178:179], s[48:49] offset:1024
	s_waitcnt vmcnt(7)
	v_pk_mul_f32 v[12:13], v[88:89], v[12:13]
	v_pk_mul_f32 v[14:15], v[90:91], v[14:15]
	v_pk_add_f32 v[36:37], v[92:93], 1.0 op_sel_hi:[1,0]
	v_pk_add_f32 v[34:35], v[94:95], 1.0 op_sel_hi:[1,0]
	v_pk_fma_f32 v[12:13], v[36:37], v[12:13], v[96:97]
	s_nop 0
	v_pk_fma_f32 v[14:15], v[34:35], v[14:15], v[98:99]
	s_nop 0
	v_cvt_pk_bf16_f32 v0, v12, v13
	s_nop 0
	v_cvt_pk_bf16_f32 v1, v14, v15

; __device__ __forceinline__ void ph_norm2(int li) {
;     ...
;     for (int row = gw; row < MR; row += NGW) {
;         const int mi = row < ML ? row >> 11 : 8;
;         if (row < ML) mod_row<0>(XL + (size_t)row * DM, nullptr, g2, md + mi * 6144 + 3 * 1024, md + mi * 6144 + 4 * 1024, H + (size_t)row * DM, lane);
;         else mod_row<4>(XC + (size_t)(row - ML) * DM, (const float*)(R + 36 * MiB) + (size_t)(row - ML) * DM, g2, md + mi * 6144 + 3 * 1024, md + mi * 6144 + 4 * 1024, H + (size_t)row * DM, lane);
	s_mov_b64 s[2:3], 0
